# dil second-round rebalance + pooling loop: 8 row loads per 4-row group hoisted, single wait
# baseline (speedup 1.0000x reference)
; __global__ void __launch_bounds__(NWAVES * 64, 2) fwd(Args args_unused) {
;     extern __shared__ __attribute__((aligned(16))) unsigned char lds[];
_Z3fwd4Args:

; #define LAS __attribute__((address_space(3)))
; __device__ __forceinline__ unsigned xb_add(unsigned* p, unsigned v) { return __hip_atomic_fetch_add(p, v, __ATOMIC_RELAXED, __HIP_MEMORY_SCOPE_AGENT); }
; __device__ __forceinline__ unsigned xb_xcc_id() { return (unsigned)__builtin_amdgcn_s_getreg((3 << 11) | 20) & 0xFu; }
; __device__ __forceinline__ KArgs kargs() { KArgs p = (KArgs)__builtin_amdgcn_kernarg_segment_ptr(); asm volatile("" : "+s"(p)); return p; }
; __global__ void __launch_bounds__(NWAVES * 64, 2) fwd(Args args_unused) {
;     ...
;     { const int tid0 = threadIdx.x; for (int u = tid0; u < (LDS_BYTES - LDSCTL_OFF) / 4; u += NWAVES * 64) ((LAS unsigned*)(ldsp + LDSCTL_OFF))[u] = 0u; }
;     __syncthreads();
;     int lo, hi; { const KArgs ka = kargs(); lo = ka->ph_lo; hi = ka->ph_hi; }
;     if (threadIdx.x == 0) { unsigned* ctl0 = (unsigned*)(kargs()->ws + WS_CTL); const unsigned x = xb_xcc_id(); volatile LAS unsigned* Mv = (volatile LAS unsigned*)(ldsp + MISC_OFF);
;         Mv[16] = x; Mv[17] = xb_add(&ctl0[CW_RANK + 64 * x], 1u); }
;     __syncthreads();
	v_lshl_add_u32 v1, v0, 2, 0
	v_add_u32_e32 v1, 0x20000, v1
	v_mov_b32_e32 v2, 0
	s_mov_b32 s77, s2
	s_mov_b64 s[84:85], s[0:1]
	ds_write2st64_b32 v1, v2, v2 offset1:8
	ds_write2st64_b32 v1, v2, v2 offset0:16 offset1:24
	v_or_b32_e32 v1, 0x800, v0
	s_mov_b64 s[2:3], -1
	s_and_saveexec_b64 s[4:5], s[2:3]
	v_lshl_add_u32 v3, v1, 2, 0
	v_add_u32_e32 v3, 0x20000, v3
	ds_write_b32 v3, v2
	s_or_b64 exec, exec, s[4:5]
	s_and_saveexec_b64 s[4:5], s[2:3]
	s_add_i32 s0, 0, 0x20000
	v_lshl_add_u32 v1, v1, 2, s0
	v_mov_b32_e32 v2, 0
	ds_write_b32 v1, v2 offset:2048
	s_or_b64 exec, exec, s[4:5]
	v_or_b32_e32 v1, 0xc00, v0
	v_cmp_gt_u32_e64 s[2:3], 7, 6
	v_cmp_gt_u32_e64 s[0:1], 7, 5
	s_and_saveexec_b64 s[4:5], s[0:1]
	v_lshl_add_u32 v2, v1, 2, 0
	v_add_u32_e32 v2, 0x20000, v2
	v_mov_b32_e32 v3, 0
	ds_write_b32 v2, v3
	s_or_b64 exec, exec, s[4:5]
	s_and_saveexec_b64 s[4:5], s[2:3]
	s_add_i32 s0, 0, 0x20000
	v_lshl_add_u32 v1, v1, 2, s0
	v_mov_b32_e32 v2, 0
	ds_write_b32 v1, v2 offset:2048
	s_or_b64 exec, exec, s[4:5]
	s_mov_b64 s[0:1], s[84:85]
	s_waitcnt lgkmcnt(0)
	s_barrier
	s_load_dwordx2 s[86:87], s[0:1], 0x78
	v_cmp_eq_u32_e64 s[88:89], 0, v0
	s_and_saveexec_b64 s[2:3], s[88:89]
	s_cbranch_execz .LBB0_12
	s_mov_b64 s[8:9], s[84:85]
	s_getreg_b32 s0, hwreg(HW_REG_XCC_ID, 0, 4)
	s_and_b32 s0, s0, 15
	s_add_i32 s1, 0, 0x20180
	s_mov_b64 s[4:5], exec
	v_mov_b32_e32 v1, s1
	v_mov_b32_e32 v2, s0
	ds_write_b32 v1, v2
	v_mbcnt_lo_u32_b32 v1, s4, 0
	v_mbcnt_hi_u32_b32 v1, s5, v1
	v_cmp_eq_u32_e32 vcc, 0, v1
	s_and_saveexec_b64 s[6:7], vcc
	s_cbranch_execz .LBB0_11
	s_load_dwordx2 s[8:9], s[8:9], 0x70
	s_lshl_b32 s0, s0, 8
	v_mov_b32_e32 v2, 0x8000
	s_waitcnt lgkmcnt(0)
	s_add_u32 s0, s8, s0
	s_addc_u32 s1, s9, 0
	s_bcnt1_i32_b64 s4, s[4:5]
	v_mov_b32_e32 v3, s4
	global_atomic_add v2, v2, v3, s[0:1] sc0

; __host__ __device__ __forceinline__ size_t img_elem(int r, int c, int K) { const int ob = (r & 15) * 64 + (c & 31) * 2; return ((size_t)((r >> 4) * (K >> 5) + (c >> 5)) * 1024 + (size_t)(ob ^ (((ob >> 9) & 1) << 5))) >> 1; }
; __device__ __forceinline__ unsigned cvt_pk_bf16(float lo, float hi) { f32x2 v = {lo, hi}; bf16x2_t b = __builtin_convertvector(v, bf16x2_t); return __builtin_bit_cast(unsigned, b); }
; __device__ __forceinline__ void unpack8(const v4u& w, float (&f)[8]) { f[0] = bf_lo(w.x); f[1] = bf_hi(w.x); f[2] = bf_lo(w.y); f[3] = bf_hi(w.y); f[4] = bf_lo(w.z); f[5] = bf_hi(w.z); f[6] = bf_lo(w.w); f[7] = bf_hi(w.w); }
; __device__ __forceinline__ void mixer_cd(const bf16* __restrict__ P, bf16* MIX, const float* __restrict__ cw  , unsigned gtid, unsigned nthr) {
;     ...
;             for (int r = 0; r < RUN; ++r) { const int t = t0 + r; float cur[8]; unpack8(*(const v4u*)(p + (size_t)r * LDP), cur);
; #pragma unroll
;                 for (int e = 0; e < 8; ++e) acc[e] += cur[e];
;                 const int cnt = (t + 1 < w) ? t + 1 : w; const float rc = 1.f / (float)cnt; v4u ov;
;                 ov.x = cvt_pk_bf16(acc[0] * rc - cur[0], acc[1] * rc - cur[1]); ov.y = cvt_pk_bf16(acc[2] * rc - cur[2], acc[3] * rc - cur[3]);
;                 ov.z = cvt_pk_bf16(acc[4] * rc - cur[4], acc[5] * rc - cur[5]); ov.w = cvt_pk_bf16(acc[6] * rc - cur[6], acc[7] * rc - cur[7]);
;                 *(v4u*)(MIX + pg8::img_elem(row0 + r, ocol, DM)) = ov;
;                 if (t - (w - 1) >= 0) { float f[8]; unpack8(*(const v4u*)(p + (size_t)(r - (w - 1)) * LDP), f);
; #pragma unroll
;                     for (int e = 0; e < 8; ++e) acc[e] -= f[e]; } }
.LBB0_423:
	v_lshl_add_u64 v[6:7], v[4:5], 0, s[16:17]
	v_add_co_u32_e32 v250, vcc, 0x34203000, v6
	s_nop 1
	v_addc_co_u32_e32 v251, vcc, 0, v7, vcc
	global_load_dwordx4 v[218:221], v[250:251], off offset:768
	v_add_co_u32_e32 v250, vcc, 0x34208000, v6
	s_nop 1
	v_addc_co_u32_e32 v251, vcc, 0, v7, vcc
	global_load_dwordx4 v[222:225], v[250:251], off offset:768
	v_add_co_u32_e32 v250, vcc, 0x3420d000, v6
	s_nop 1
	v_addc_co_u32_e32 v251, vcc, 0, v7, vcc
	global_load_dwordx4 v[226:229], v[250:251], off offset:768
	v_add_co_u32_e32 v250, vcc, 0x34212000, v6
	s_nop 1
	v_addc_co_u32_e32 v251, vcc, 0, v7, vcc
	global_load_dwordx4 v[230:233], v[250:251], off offset:768
	v_lshl_add_u64 v[252:253], v[2:3], 0, s[16:17]
	v_add_co_u32_e32 v250, vcc, 0x34208000, v252
	s_nop 1
	v_addc_co_u32_e32 v251, vcc, 0, v253, vcc
	v_add_u32_e32 v217, -4, v24
	v_cmp_ge_i32_e32 vcc, v217, v77
	s_and_saveexec_b64 s[98:99], vcc
	s_cbranch_execz .Lpool_lv0
	global_load_dwordx4 v[234:237], v[250:251], off offset:768
.Lpool_lv0:
	s_or_b64 exec, exec, s[98:99]
	v_add_co_u32_e32 v250, vcc, 0x3420d000, v252
	s_nop 1
	v_addc_co_u32_e32 v251, vcc, 0, v253, vcc
	v_add_u32_e32 v217, -3, v24
	v_cmp_ge_i32_e32 vcc, v217, v77
	s_and_saveexec_b64 s[98:99], vcc
	s_cbranch_execz .Lpool_lv1
	global_load_dwordx4 v[238:241], v[250:251], off offset:768
.Lpool_lv1:
	s_or_b64 exec, exec, s[98:99]
	v_add_co_u32_e32 v250, vcc, 0x34212000, v252
	s_nop 1
	v_addc_co_u32_e32 v251, vcc, 0, v253, vcc
	v_add_u32_e32 v217, -2, v24
	v_cmp_ge_i32_e32 vcc, v217, v77
	s_and_saveexec_b64 s[98:99], vcc
	s_cbranch_execz .Lpool_lv2
	global_load_dwordx4 v[242:245], v[250:251], off offset:768
.Lpool_lv2:
	s_or_b64 exec, exec, s[98:99]
	v_add_co_u32_e32 v250, vcc, 0x34217000, v252
	s_nop 1
	v_addc_co_u32_e32 v251, vcc, 0, v253, vcc
	v_add_u32_e32 v217, -1, v24
	v_cmp_ge_i32_e32 vcc, v217, v77
	s_and_saveexec_b64 s[98:99], vcc
	s_cbranch_execz .Lpool_lv3
	global_load_dwordx4 v[246:249], v[250:251], off offset:768
.Lpool_lv3:
	s_or_b64 exec, exec, s[98:99]
	s_waitcnt vmcnt(0)
	v_add_co_u32_e32 v8, vcc, 0x34203000, v6
	v_add_u32_e32 v20, -3, v24
	s_nop 0
	v_addc_co_u32_e32 v9, vcc, 0, v7, vcc
	v_min_u32_e32 v9, v20, v76
	v_cvt_f32_u32_e32 v18, v9
	s_and_b32 s2, s1, 16
	v_add_u32_e32 v8, -4, v24
	v_xad_u32 v178, v23, s2, v22
	v_div_scale_f32 v19, s[18:19], v18, v18, 1.0
	v_rcp_f32_e32 v21, v19
	v_div_scale_f32 v25, vcc, 1.0, v18, 1.0
	v_cmp_ge_i32_e64 s[14:15], v8, v77
	v_fma_f32 v30, -v19, v21, 1.0
	v_fmac_f32_e32 v21, v30, v21
	v_mul_f32_e32 v30, v25, v21
	v_fma_f32 v31, -v19, v30, v25
	v_fmac_f32_e32 v30, v31, v21
	v_fma_f32 v19, -v19, v30, v25
	v_div_fmas_f32 v19, v19, v21, v30
	v_div_fixup_f32 v30, v19, v18, 1.0
	v_lshl_add_u64 v[8:9], v[178:179], 1, s[24:25]
	v_mov_b32_e32 v26, v218
	v_mov_b32_e32 v27, v219
	v_mov_b32_e32 v28, v220
	v_mov_b32_e32 v29, v221
	v_lshlrev_b32_e32 v32, 16, v26
	v_and_b32_e32 v33, 0xffff0000, v26
	v_lshlrev_b32_e32 v26, 16, v27
	v_and_b32_e32 v27, 0xffff0000, v27
	v_lshlrev_b32_e32 v34, 16, v28
	v_and_b32_e32 v35, 0xffff0000, v28
	v_lshlrev_b32_e32 v28, 16, v29
	v_and_b32_e32 v29, 0xffff0000, v29
	v_pk_add_f32 v[18:19], v[10:11], v[32:33]
	v_pk_add_f32 v[12:13], v[12:13], v[26:27]
	v_pk_add_f32 v[10:11], v[14:15], v[34:35]
	v_pk_add_f32 v[14:15], v[16:17], v[28:29]
	v_pk_fma_f32 v[16:17], v[30:31], v[18:19], v[32:33] op_sel_hi:[0,1,1] neg_lo:[0,0,1] neg_hi:[0,0,1]
	v_pk_fma_f32 v[32:33], v[30:31], v[12:13], v[26:27] op_sel_hi:[0,1,1] neg_lo:[0,0,1] neg_hi:[0,0,1]
	v_pk_fma_f32 v[34:35], v[30:31], v[10:11], v[34:35] op_sel_hi:[0,1,1] neg_lo:[0,0,1] neg_hi:[0,0,1]
	v_pk_fma_f32 v[30:31], v[30:31], v[14:15], v[28:29] op_sel_hi:[0,1,1] neg_lo:[0,0,1] neg_hi:[0,0,1]
	v_cvt_pk_bf16_f32 v26, v16, v17
	v_cvt_pk_bf16_f32 v27, v32, v33
	v_cvt_pk_bf16_f32 v28, v34, v35
	v_cvt_pk_bf16_f32 v29, v30, v31
	global_store_dwordx4 v[8:9], v[26:29], off
	v_lshl_add_u64 v[8:9], v[2:3], 0, s[16:17]
	s_and_saveexec_b64 s[18:19], s[14:15]
	s_cbranch_execz .LBB0_425
	v_add_co_u32_e32 v16, vcc, 0x34208000, v8
	s_nop 1
	v_addc_co_u32_e32 v17, vcc, 0, v9, vcc
	v_mov_b32_e32 v26, v234
	v_mov_b32_e32 v27, v235
	v_mov_b32_e32 v28, v236
	v_mov_b32_e32 v29, v237
	v_lshlrev_b32_e32 v16, 16, v26
	v_and_b32_e32 v17, 0xffff0000, v26
	v_lshlrev_b32_e32 v26, 16, v27
	v_and_b32_e32 v27, 0xffff0000, v27
	v_lshlrev_b32_e32 v30, 16, v28
	v_and_b32_e32 v31, 0xffff0000, v28
	v_lshlrev_b32_e32 v28, 16, v29
	v_and_b32_e32 v29, 0xffff0000, v29
	v_pk_add_f32 v[18:19], v[18:19], v[16:17] neg_lo:[0,1] neg_hi:[0,1]
	v_pk_add_f32 v[12:13], v[12:13], v[26:27] neg_lo:[0,1] neg_hi:[0,1]
	v_pk_add_f32 v[10:11], v[10:11], v[30:31] neg_lo:[0,1] neg_hi:[0,1]
	v_pk_add_f32 v[14:15], v[14:15], v[28:29] neg_lo:[0,1] neg_hi:[0,1]
; __host__ __device__ __forceinline__ size_t img_elem(int r, int c, int K) { const int ob = (r & 15) * 64 + (c & 31) * 2; return ((size_t)((r >> 4) * (K >> 5) + (c >> 5)) * 1024 + (size_t)(ob ^ (((ob >> 9) & 1) << 5))) >> 1; }
; __device__ __forceinline__ unsigned cvt_pk_bf16(float lo, float hi) { f32x2 v = {lo, hi}; bf16x2_t b = __builtin_convertvector(v, bf16x2_t); return __builtin_bit_cast(unsigned, b); }
; __device__ __forceinline__ void unpack8(const v4u& w, float (&f)[8]) { f[0] = bf_lo(w.x); f[1] = bf_hi(w.x); f[2] = bf_lo(w.y); f[3] = bf_hi(w.y); f[4] = bf_lo(w.z); f[5] = bf_hi(w.z); f[6] = bf_lo(w.w); f[7] = bf_hi(w.w); }
; __device__ __forceinline__ void mixer_cd(const bf16* __restrict__ P, bf16* MIX, const float* __restrict__ cw  , unsigned gtid, unsigned nthr) {
;     ...
;             for (int r = 0; r < RUN; ++r) { const int t = t0 + r; float cur[8]; unpack8(*(const v4u*)(p + (size_t)r * LDP), cur);
; #pragma unroll
;                 for (int e = 0; e < 8; ++e) acc[e] += cur[e];
;                 const int cnt = (t + 1 < w) ? t + 1 : w; const float rc = 1.f / (float)cnt; v4u ov;
;                 ov.x = cvt_pk_bf16(acc[0] * rc - cur[0], acc[1] * rc - cur[1]); ov.y = cvt_pk_bf16(acc[2] * rc - cur[2], acc[3] * rc - cur[3]);
;                 ov.z = cvt_pk_bf16(acc[4] * rc - cur[4], acc[5] * rc - cur[5]); ov.w = cvt_pk_bf16(acc[6] * rc - cur[6], acc[7] * rc - cur[7]);
;                 *(v4u*)(MIX + pg8::img_elem(row0 + r, ocol, DM)) = ov;
;                 if (t - (w - 1) >= 0) { float f[8]; unpack8(*(const v4u*)(p + (size_t)(r - (w - 1)) * LDP), f);
; #pragma unroll
;                     for (int e = 0; e < 8; ++e) acc[e] -= f[e]; } }
.LBB0_425:
	s_or_b64 exec, exec, s[18:19]
	v_add_co_u32_e32 v16, vcc, 0x34208000, v6
	v_add_u32_e32 v25, -2, v24
	s_nop 0
	v_addc_co_u32_e32 v17, vcc, 0, v7, vcc
	v_min_u32_e32 v16, v25, v76
	v_cvt_f32_u32_e32 v16, v16
	v_add_u32_e32 v17, 32, v23
	v_xad_u32 v178, v17, s2, v22
	v_lshl_add_u64 v[30:31], v[178:179], 1, s[24:25]
	v_div_scale_f32 v17, s[14:15], v16, v16, 1.0
	v_rcp_f32_e32 v21, v17
	v_div_scale_f32 v32, vcc, 1.0, v16, 1.0
	v_fma_f32 v33, -v17, v21, 1.0
	v_fmac_f32_e32 v21, v33, v21
	v_mul_f32_e32 v33, v32, v21
	v_fma_f32 v34, -v17, v33, v32
	v_fmac_f32_e32 v33, v34, v21
	v_fma_f32 v17, -v17, v33, v32
	v_div_fmas_f32 v17, v17, v21, v33
	v_div_fixup_f32 v32, v17, v16, 1.0
	v_cmp_ge_i32_e32 vcc, v20, v77
	v_mov_b32_e32 v26, v222
	v_mov_b32_e32 v27, v223
	v_mov_b32_e32 v28, v224
	v_mov_b32_e32 v29, v225
	v_lshlrev_b32_e32 v34, 16, v26
	v_and_b32_e32 v35, 0xffff0000, v26
	v_lshlrev_b32_e32 v26, 16, v27
	v_and_b32_e32 v27, 0xffff0000, v27
	v_lshlrev_b32_e32 v36, 16, v28
	v_and_b32_e32 v37, 0xffff0000, v28
	v_lshlrev_b32_e32 v28, 16, v29
	v_and_b32_e32 v29, 0xffff0000, v29
	v_pk_add_f32 v[16:17], v[18:19], v[34:35]
	v_pk_add_f32 v[12:13], v[12:13], v[26:27]
	v_pk_add_f32 v[10:11], v[10:11], v[36:37]
	v_pk_add_f32 v[14:15], v[14:15], v[28:29]
	v_pk_fma_f32 v[18:19], v[32:33], v[16:17], v[34:35] op_sel_hi:[0,1,1] neg_lo:[0,0,1] neg_hi:[0,0,1]
	v_pk_fma_f32 v[34:35], v[32:33], v[12:13], v[26:27] op_sel_hi:[0,1,1] neg_lo:[0,0,1] neg_hi:[0,0,1]
	v_pk_fma_f32 v[36:37], v[32:33], v[10:11], v[36:37] op_sel_hi:[0,1,1] neg_lo:[0,0,1] neg_hi:[0,0,1]
	v_pk_fma_f32 v[32:33], v[32:33], v[14:15], v[28:29] op_sel_hi:[0,1,1] neg_lo:[0,0,1] neg_hi:[0,0,1]
	v_cvt_pk_bf16_f32 v26, v18, v19
	v_cvt_pk_bf16_f32 v27, v34, v35
	v_cvt_pk_bf16_f32 v28, v36, v37
	v_cvt_pk_bf16_f32 v29, v32, v33
	global_store_dwordx4 v[30:31], v[26:29], off
	s_and_saveexec_b64 s[14:15], vcc
	s_cbranch_execz .LBB0_427
	v_add_co_u32_e32 v18, vcc, 0x3420d000, v8
	s_nop 1
	v_addc_co_u32_e32 v19, vcc, 0, v9, vcc
	v_mov_b32_e32 v18, v238
	v_mov_b32_e32 v19, v239
	v_mov_b32_e32 v20, v240
	v_mov_b32_e32 v21, v241
	v_lshlrev_b32_e32 v26, 16, v18
	v_and_b32_e32 v27, 0xffff0000, v18
	v_lshlrev_b32_e32 v18, 16, v19
	v_and_b32_e32 v19, 0xffff0000, v19
	v_lshlrev_b32_e32 v28, 16, v20
	v_and_b32_e32 v29, 0xffff0000, v20
	v_lshlrev_b32_e32 v20, 16, v21
	v_and_b32_e32 v21, 0xffff0000, v21
	v_pk_add_f32 v[16:17], v[16:17], v[26:27] neg_lo:[0,1] neg_hi:[0,1]
	v_pk_add_f32 v[12:13], v[12:13], v[18:19] neg_lo:[0,1] neg_hi:[0,1]
	v_pk_add_f32 v[10:11], v[10:11], v[28:29] neg_lo:[0,1] neg_hi:[0,1]
	v_pk_add_f32 v[14:15], v[14:15], v[20:21] neg_lo:[0,1] neg_hi:[0,1]
; __host__ __device__ __forceinline__ size_t img_elem(int r, int c, int K) { const int ob = (r & 15) * 64 + (c & 31) * 2; return ((size_t)((r >> 4) * (K >> 5) + (c >> 5)) * 1024 + (size_t)(ob ^ (((ob >> 9) & 1) << 5))) >> 1; }
; __device__ __forceinline__ unsigned cvt_pk_bf16(float lo, float hi) { f32x2 v = {lo, hi}; bf16x2_t b = __builtin_convertvector(v, bf16x2_t); return __builtin_bit_cast(unsigned, b); }
; __device__ __forceinline__ void unpack8(const v4u& w, float (&f)[8]) { f[0] = bf_lo(w.x); f[1] = bf_hi(w.x); f[2] = bf_lo(w.y); f[3] = bf_hi(w.y); f[4] = bf_lo(w.z); f[5] = bf_hi(w.z); f[6] = bf_lo(w.w); f[7] = bf_hi(w.w); }
; __device__ __forceinline__ void mixer_cd(const bf16* __restrict__ P, bf16* MIX, const float* __restrict__ cw  , unsigned gtid, unsigned nthr) {
;     ...
;             for (int r = 0; r < RUN; ++r) { const int t = t0 + r; float cur[8]; unpack8(*(const v4u*)(p + (size_t)r * LDP), cur);
; #pragma unroll
;                 for (int e = 0; e < 8; ++e) acc[e] += cur[e];
;                 const int cnt = (t + 1 < w) ? t + 1 : w; const float rc = 1.f / (float)cnt; v4u ov;
;                 ov.x = cvt_pk_bf16(acc[0] * rc - cur[0], acc[1] * rc - cur[1]); ov.y = cvt_pk_bf16(acc[2] * rc - cur[2], acc[3] * rc - cur[3]);
;                 ov.z = cvt_pk_bf16(acc[4] * rc - cur[4], acc[5] * rc - cur[5]); ov.w = cvt_pk_bf16(acc[6] * rc - cur[6], acc[7] * rc - cur[7]);
;                 *(v4u*)(MIX + pg8::img_elem(row0 + r, ocol, DM)) = ov;
;                 if (t - (w - 1) >= 0) { float f[8]; unpack8(*(const v4u*)(p + (size_t)(r - (w - 1)) * LDP), f);
; #pragma unroll
;                     for (int e = 0; e < 8; ++e) acc[e] -= f[e]; } }
.LBB0_427:
	s_or_b64 exec, exec, s[14:15]
	v_add_co_u32_e32 v18, vcc, 0x3420d000, v6
	v_add_u32_e32 v26, -1, v24
	s_nop 0
	v_addc_co_u32_e32 v19, vcc, 0, v7, vcc
	v_min_u32_e32 v27, v26, v76
	v_cvt_f32_u32_e32 v27, v27
	v_add_u32_e32 v28, 64, v23
	v_xad_u32 v178, v28, s2, v22
	v_lshl_add_u64 v[32:33], v[178:179], 1, s[24:25]
	v_div_scale_f32 v28, s[14:15], v27, v27, 1.0
	v_rcp_f32_e32 v29, v28
	v_div_scale_f32 v30, vcc, 1.0, v27, 1.0
	v_fma_f32 v31, -v28, v29, 1.0
	v_fmac_f32_e32 v29, v31, v29
	v_mul_f32_e32 v31, v30, v29
	v_fma_f32 v34, -v28, v31, v30
	v_fmac_f32_e32 v31, v34, v29
	v_fma_f32 v28, -v28, v31, v30
	v_div_fmas_f32 v28, v28, v29, v31
	v_div_fixup_f32 v28, v28, v27, 1.0
	v_cmp_ge_i32_e32 vcc, v25, v77
	v_mov_b32_e32 v18, v226
	v_mov_b32_e32 v19, v227
	v_mov_b32_e32 v20, v228
	v_mov_b32_e32 v21, v229
	v_lshlrev_b32_e32 v30, 16, v18
	v_and_b32_e32 v31, 0xffff0000, v18
	v_lshlrev_b32_e32 v34, 16, v19
	v_and_b32_e32 v35, 0xffff0000, v19
	v_lshlrev_b32_e32 v36, 16, v20
	v_and_b32_e32 v37, 0xffff0000, v20
	v_lshlrev_b32_e32 v38, 16, v21
	v_and_b32_e32 v39, 0xffff0000, v21
	v_pk_add_f32 v[18:19], v[16:17], v[30:31]
	v_pk_add_f32 v[12:13], v[12:13], v[34:35]
	v_pk_add_f32 v[16:17], v[10:11], v[36:37]
	v_pk_add_f32 v[20:21], v[14:15], v[38:39]
	v_pk_fma_f32 v[10:11], v[28:29], v[18:19], v[30:31] op_sel_hi:[0,1,1] neg_lo:[0,0,1] neg_hi:[0,0,1]
	v_pk_fma_f32 v[14:15], v[28:29], v[12:13], v[34:35] op_sel_hi:[0,1,1] neg_lo:[0,0,1] neg_hi:[0,0,1]
	v_pk_fma_f32 v[30:31], v[28:29], v[16:17], v[36:37] op_sel_hi:[0,1,1] neg_lo:[0,0,1] neg_hi:[0,0,1]
	v_pk_fma_f32 v[34:35], v[28:29], v[20:21], v[38:39] op_sel_hi:[0,1,1] neg_lo:[0,0,1] neg_hi:[0,0,1]
	v_cvt_pk_bf16_f32 v28, v10, v11
	v_cvt_pk_bf16_f32 v29, v14, v15
	v_cvt_pk_bf16_f32 v30, v30, v31
	v_cvt_pk_bf16_f32 v31, v34, v35
	global_store_dwordx4 v[32:33], v[28:31], off
	s_and_saveexec_b64 s[14:15], vcc
	s_cbranch_execz .LBB0_429
	v_add_co_u32_e32 v10, vcc, 0x34212000, v8
	s_nop 1
	v_addc_co_u32_e32 v11, vcc, 0, v9, vcc
	v_mov_b32_e32 v28, v242
	v_mov_b32_e32 v29, v243
	v_mov_b32_e32 v30, v244
	v_mov_b32_e32 v31, v245
	v_lshlrev_b32_e32 v10, 16, v28
	v_and_b32_e32 v11, 0xffff0000, v28
	v_lshlrev_b32_e32 v14, 16, v29
	v_and_b32_e32 v15, 0xffff0000, v29
	v_lshlrev_b32_e32 v28, 16, v30
	v_and_b32_e32 v29, 0xffff0000, v30
	v_lshlrev_b32_e32 v30, 16, v31
	v_and_b32_e32 v31, 0xffff0000, v31
	v_pk_add_f32 v[18:19], v[18:19], v[10:11] neg_lo:[0,1] neg_hi:[0,1]
	v_pk_add_f32 v[12:13], v[12:13], v[14:15] neg_lo:[0,1] neg_hi:[0,1]
	v_pk_add_f32 v[16:17], v[16:17], v[28:29] neg_lo:[0,1] neg_hi:[0,1]
	v_pk_add_f32 v[20:21], v[20:21], v[30:31] neg_lo:[0,1] neg_hi:[0,1]
.LBB0_429:
	s_or_b64 exec, exec, s[14:15]
	v_add_co_u32_e32 v6, vcc, 0x34212000, v6
	s_nop 1
	v_addc_co_u32_e32 v7, vcc, 0, v7, vcc
	v_min_u32_e32 v6, v24, v76
	v_cvt_f32_u32_e32 v10, v6
	v_add_u32_e32 v6, 0x60, v23
	v_xad_u32 v178, v6, s2, v22
	v_lshl_add_u64 v[6:7], v[178:179], 1, s[24:25]
	v_div_scale_f32 v11, s[2:3], v10, v10, 1.0
	v_rcp_f32_e32 v14, v11
	v_div_scale_f32 v15, vcc, 1.0, v10, 1.0
	v_fma_f32 v25, -v11, v14, 1.0
	v_fmac_f32_e32 v14, v25, v14
	v_mul_f32_e32 v25, v15, v14
	v_fma_f32 v27, -v11, v25, v15
	v_fmac_f32_e32 v25, v27, v14
	v_fma_f32 v11, -v11, v25, v15
	v_div_fmas_f32 v11, v11, v14, v25
	v_div_fixup_f32 v32, v11, v10, 1.0
	v_cmp_ge_i32_e32 vcc, v26, v77
	v_mov_b32_e32 v28, v230
	v_mov_b32_e32 v29, v231
	v_mov_b32_e32 v30, v232
	v_mov_b32_e32 v31, v233
	v_lshlrev_b32_e32 v34, 16, v28
	v_and_b32_e32 v35, 0xffff0000, v28
	v_lshlrev_b32_e32 v28, 16, v29
	v_and_b32_e32 v29, 0xffff0000, v29
	v_lshlrev_b32_e32 v36, 16, v30
	v_and_b32_e32 v37, 0xffff0000, v30
	v_lshlrev_b32_e32 v30, 16, v31
	v_and_b32_e32 v31, 0xffff0000, v31
	v_pk_add_f32 v[10:11], v[18:19], v[34:35]
	v_pk_add_f32 v[12:13], v[12:13], v[28:29]
	v_pk_add_f32 v[14:15], v[16:17], v[36:37]
	v_pk_add_f32 v[16:17], v[20:21], v[30:31]
	v_pk_fma_f32 v[18:19], v[32:33], v[10:11], v[34:35] op_sel_hi:[0,1,1] neg_lo:[0,0,1] neg_hi:[0,0,1]
	v_pk_fma_f32 v[20:21], v[32:33], v[12:13], v[28:29] op_sel_hi:[0,1,1] neg_lo:[0,0,1] neg_hi:[0,0,1]
	v_pk_fma_f32 v[28:29], v[32:33], v[14:15], v[36:37] op_sel_hi:[0,1,1] neg_lo:[0,0,1] neg_hi:[0,0,1]
	v_pk_fma_f32 v[30:31], v[32:33], v[16:17], v[30:31] op_sel_hi:[0,1,1] neg_lo:[0,0,1] neg_hi:[0,0,1]
	v_cvt_pk_bf16_f32 v18, v18, v19
	v_cvt_pk_bf16_f32 v19, v20, v21
	v_cvt_pk_bf16_f32 v20, v28, v29
	v_cvt_pk_bf16_f32 v21, v30, v31
	global_store_dwordx4 v[6:7], v[18:21], off
	s_and_saveexec_b64 s[14:15], vcc
	s_cbranch_execz .LBB0_422
	v_add_co_u32_e32 v6, vcc, 0x34217000, v8
	s_nop 1
	v_addc_co_u32_e32 v7, vcc, 0, v9, vcc
	v_mov_b32_e32 v6, v246
	v_mov_b32_e32 v7, v247
	v_mov_b32_e32 v8, v248
	v_mov_b32_e32 v9, v249
	v_lshlrev_b32_e32 v18, 16, v6
	v_and_b32_e32 v19, 0xffff0000, v6
	v_lshlrev_b32_e32 v6, 16, v7
	v_and_b32_e32 v7, 0xffff0000, v7
	v_lshlrev_b32_e32 v20, 16, v8
	v_and_b32_e32 v21, 0xffff0000, v8
	v_lshlrev_b32_e32 v8, 16, v9
	v_and_b32_e32 v9, 0xffff0000, v9
	v_pk_add_f32 v[10:11], v[10:11], v[18:19] neg_lo:[0,1] neg_hi:[0,1]
	v_pk_add_f32 v[12:13], v[12:13], v[6:7] neg_lo:[0,1] neg_hi:[0,1]
	v_pk_add_f32 v[14:15], v[14:15], v[20:21] neg_lo:[0,1] neg_hi:[0,1]
	v_pk_add_f32 v[16:17], v[16:17], v[8:9] neg_lo:[0,1] neg_hi:[0,1]
	s_branch .LBB0_422
